# attention loop: the five scalar instructions that advance the V ring offsets moved from in front of the per-step barrier to right behind the V LDS-DMA issue (mid-step)
# speedup vs baseline: 1.0071x; 1.0023x over previous
; __device__ __forceinline__ void attn_unit(const Args& a, int l, int b, int h, int R0, bool special, LAS unsigned char* lds, float kb, int wv, bool pre, bool hasn, int nb, int nh, int nR0) {
;     ...
;     if (wave >= 4) __builtin_amdgcn_s_setprio(1);
.Lfa_as_nov:
	s_add_u32 s34, s34, 0x80
	s_addc_u32 s35, s35, 0
	s_mov_b32 s1, s30
	s_add_i32 s30, s30, 0x2400
	s_cmp_eq_u32 s30, 0x6c00
	s_cselect_b32 s30, 0, s30
	s_mov_b32 s31, s1
	v_add_f32_e32 v249, v249, v101
	v_exp_f32_e32 v103, v103
	v_add_f32_e32 v250, v250, v102
	v_add_f32_e32 v251, v251, v103
	s_waitcnt lgkmcnt(10)
	v_mfma_f32_32x32x16_bf16 v[128:143], v[2:5], v[156:159], v[32:47]
	v_cvt_pk_bf16_f32 v96, v96, v97
	v_cvt_pk_bf16_f32 v97, v98, v99
	v_cvt_pk_bf16_f32 v98, v100, v101
	v_cvt_pk_bf16_f32 v99, v102, v103
	v_mfma_f32_32x32x16_bf16 v[112:127], v[6:9], v[156:159], v[32:47]
	ds_read_b128 v[2:5], v231
	ds_read_b128 v[6:9], v231 offset:4608
	v_exp_f32_e32 v104, v104
	v_exp_f32_e32 v105, v105
	v_add_f32_e32 v248, v248, v104
	v_exp_f32_e32 v106, v106
	s_waitcnt lgkmcnt(10)
	v_mfma_f32_32x32x16_bf16 v[128:143], v[10:13], v[160:163], v[128:143]
	v_add_f32_e32 v249, v249, v105
	v_exp_f32_e32 v107, v107
	v_add_f32_e32 v250, v250, v106
	v_exp_f32_e32 v108, v108
	v_mfma_f32_32x32x16_bf16 v[112:127], v[198:201], v[160:163], v[112:127]
	ds_read_b128 v[10:13], v231 offset:32
	ds_read_b128 v[198:201], v231 offset:4640
	v_add_f32_e32 v251, v251, v107
	v_exp_f32_e32 v109, v109
	v_add_f32_e32 v248, v248, v108
	v_exp_f32_e32 v110, v110
	s_waitcnt lgkmcnt(10)
	v_mfma_f32_32x32x16_bf16 v[128:143], v[202:205], v[164:167], v[128:143]
	v_add_f32_e32 v249, v249, v109
	v_exp_f32_e32 v111, v111
	v_add_f32_e32 v250, v250, v110
	v_add_f32_e32 v251, v251, v111
	v_mfma_f32_32x32x16_bf16 v[112:127], v[206:209], v[164:167], v[112:127]
	v_cvt_pk_bf16_f32 v104, v104, v105
	v_cvt_pk_bf16_f32 v105, v106, v107
	v_cvt_pk_bf16_f32 v106, v108, v109
	v_cvt_pk_bf16_f32 v107, v110, v111
	s_waitcnt lgkmcnt(8)
	v_mfma_f32_32x32x16_bf16 v[128:143], v[210:213], v[144:147], v[128:143]
	v_exp_f32_e32 v80, v80
	v_exp_f32_e32 v81, v81
	v_add_f32_e32 v248, v248, v80
	v_exp_f32_e32 v82, v82
	v_mfma_f32_32x32x16_bf16 v[112:127], v[214:217], v[144:147], v[112:127]
	ds_read_b128 v[210:213], v231 offset:64
	ds_read_b128 v[214:217], v231 offset:4672
	v_add_f32_e32 v249, v249, v81
	v_exp_f32_e32 v83, v83
	v_add_f32_e32 v250, v250, v82
	v_exp_f32_e32 v84, v84
	s_waitcnt lgkmcnt(8)
	v_mfma_f32_32x32x16_bf16 v[128:143], v[218:221], v[148:151], v[128:143]
	v_add_f32_e32 v251, v251, v83
	v_exp_f32_e32 v85, v85
	v_add_f32_e32 v248, v248, v84
	v_exp_f32_e32 v86, v86
	v_mfma_f32_32x32x16_bf16 v[112:127], v[222:225], v[148:151], v[112:127]
	ds_read_b128 v[218:221], v231 offset:96
	ds_read_b128 v[222:225], v231 offset:4704
	v_add_f32_e32 v249, v249, v85
	v_exp_f32_e32 v87, v87
	v_add_f32_e32 v250, v250, v86
	v_add_f32_e32 v251, v251, v87
	s_waitcnt lgkmcnt(8)
	v_mfma_f32_32x32x16_bf16 v[128:143], v[234:237], v[152:155], v[128:143]
	v_exp_f32_e32 v88, v88
	v_exp_f32_e32 v89, v89
	v_add_f32_e32 v248, v248, v88
	v_exp_f32_e32 v90, v90
	v_mfma_f32_32x32x16_bf16 v[112:127], v[238:241], v[152:155], v[112:127]
	v_add_f32_e32 v249, v249, v89
	v_exp_f32_e32 v91, v91
	v_add_f32_e32 v250, v250, v90
	v_exp_f32_e32 v92, v92
	s_waitcnt lgkmcnt(6)
	v_mfma_f32_32x32x16_bf16 v[64:79], v[2:5], v[96:99], v[64:79]
	v_add_f32_e32 v251, v251, v91
	v_exp_f32_e32 v93, v93
	v_add_f32_e32 v248, v248, v92
	v_exp_f32_e32 v94, v94
	v_mfma_f32_32x32x16_bf16 v[48:63], v[6:9], v[96:99], v[48:63]
	v_add_f32_e32 v249, v249, v93
	v_exp_f32_e32 v95, v95
	v_add_f32_e32 v250, v250, v94
	v_add_f32_e32 v251, v251, v95
	s_waitcnt lgkmcnt(4)
	v_mfma_f32_32x32x16_bf16 v[64:79], v[10:13], v[104:107], v[64:79]
	v_cvt_pk_bf16_f32 v234, v80, v81
	v_cvt_pk_bf16_f32 v235, v82, v83
	v_cvt_pk_bf16_f32 v236, v84, v85
	v_cvt_pk_bf16_f32 v237, v86, v87
	v_mfma_f32_32x32x16_bf16 v[48:63], v[198:201], v[104:107], v[48:63]
	v_cvt_pk_bf16_f32 v238, v88, v89
	v_cvt_pk_bf16_f32 v239, v90, v91
	v_cvt_pk_bf16_f32 v240, v92, v93
	v_cvt_pk_bf16_f32 v241, v94, v95
	s_cmp_eq_u32 s75, 3
	s_cbranch_scc1 .Lfa_as_w3
	s_cmp_eq_u32 s75, 2
	s_cbranch_scc1 .Lfa_as_w2
	s_waitcnt vmcnt(4)
	s_branch .Lfa_as_wj

; __device__ __forceinline__ void attn_unit(const Args& a, int l, int b, int h, int R0, bool special, LAS unsigned char* lds, float kb, int wv, bool pre, bool hasn, int nb, int nh, int nR0) {
;     ...
;     if (wave >= 4) __builtin_amdgcn_s_setprio(1);
.Lfa_bs_nov:
	s_add_u32 s34, s34, 0x80
	s_addc_u32 s35, s35, 0
	s_mov_b32 s1, s30
	s_add_i32 s30, s30, 0x2400
	s_cmp_eq_u32 s30, 0x6c00
	s_cselect_b32 s30, 0, s30
	s_mov_b32 s31, s1
	v_add_f32_e32 v249, v249, v133
	v_exp_f32_e32 v135, v135
	v_add_f32_e32 v250, v250, v134
	v_add_f32_e32 v251, v251, v135
	s_waitcnt lgkmcnt(10)
	v_mfma_f32_32x32x16_bf16 v[96:111], v[2:5], v[156:159], v[32:47]
	v_cvt_pk_bf16_f32 v128, v128, v129
	v_cvt_pk_bf16_f32 v129, v130, v131
	v_cvt_pk_bf16_f32 v130, v132, v133
	v_cvt_pk_bf16_f32 v131, v134, v135
	v_mfma_f32_32x32x16_bf16 v[80:95], v[6:9], v[156:159], v[32:47]
	ds_read_b128 v[2:5], v231
	ds_read_b128 v[6:9], v231 offset:4608
	v_exp_f32_e32 v136, v136
	v_exp_f32_e32 v137, v137
	v_add_f32_e32 v248, v248, v136
	v_exp_f32_e32 v138, v138
	s_waitcnt lgkmcnt(10)
	v_mfma_f32_32x32x16_bf16 v[96:111], v[10:13], v[160:163], v[96:111]
	v_add_f32_e32 v249, v249, v137
	v_exp_f32_e32 v139, v139
	v_add_f32_e32 v250, v250, v138
	v_exp_f32_e32 v140, v140
	v_mfma_f32_32x32x16_bf16 v[80:95], v[198:201], v[160:163], v[80:95]
	ds_read_b128 v[10:13], v231 offset:32
	ds_read_b128 v[198:201], v231 offset:4640
	v_add_f32_e32 v251, v251, v139
	v_exp_f32_e32 v141, v141
	v_add_f32_e32 v248, v248, v140
	v_exp_f32_e32 v142, v142
	s_waitcnt lgkmcnt(10)
	v_mfma_f32_32x32x16_bf16 v[96:111], v[202:205], v[164:167], v[96:111]
	v_add_f32_e32 v249, v249, v141
	v_exp_f32_e32 v143, v143
	v_add_f32_e32 v250, v250, v142
	v_add_f32_e32 v251, v251, v143
	v_mfma_f32_32x32x16_bf16 v[80:95], v[206:209], v[164:167], v[80:95]
	v_cvt_pk_bf16_f32 v136, v136, v137
	v_cvt_pk_bf16_f32 v137, v138, v139
	v_cvt_pk_bf16_f32 v138, v140, v141
	v_cvt_pk_bf16_f32 v139, v142, v143
	s_waitcnt lgkmcnt(8)
	v_mfma_f32_32x32x16_bf16 v[96:111], v[210:213], v[144:147], v[96:111]
	v_exp_f32_e32 v112, v112
	v_exp_f32_e32 v113, v113
	v_add_f32_e32 v248, v248, v112
	v_exp_f32_e32 v114, v114
	v_mfma_f32_32x32x16_bf16 v[80:95], v[214:217], v[144:147], v[80:95]
	ds_read_b128 v[210:213], v231 offset:64
	ds_read_b128 v[214:217], v231 offset:4672
	v_add_f32_e32 v249, v249, v113
	v_exp_f32_e32 v115, v115
	v_add_f32_e32 v250, v250, v114
	v_exp_f32_e32 v116, v116
	s_waitcnt lgkmcnt(8)
	v_mfma_f32_32x32x16_bf16 v[96:111], v[218:221], v[148:151], v[96:111]
	v_add_f32_e32 v251, v251, v115
	v_exp_f32_e32 v117, v117
	v_add_f32_e32 v248, v248, v116
	v_exp_f32_e32 v118, v118
	v_mfma_f32_32x32x16_bf16 v[80:95], v[222:225], v[148:151], v[80:95]
	ds_read_b128 v[218:221], v231 offset:96
	ds_read_b128 v[222:225], v231 offset:4704
	v_add_f32_e32 v249, v249, v117
	v_exp_f32_e32 v119, v119
	v_add_f32_e32 v250, v250, v118
	v_add_f32_e32 v251, v251, v119
	s_waitcnt lgkmcnt(8)
	v_mfma_f32_32x32x16_bf16 v[96:111], v[234:237], v[152:155], v[96:111]
	v_exp_f32_e32 v120, v120
	v_exp_f32_e32 v121, v121
	v_add_f32_e32 v248, v248, v120
	v_exp_f32_e32 v122, v122
	v_mfma_f32_32x32x16_bf16 v[80:95], v[238:241], v[152:155], v[80:95]
	v_add_f32_e32 v249, v249, v121
	v_exp_f32_e32 v123, v123
	v_add_f32_e32 v250, v250, v122
	v_exp_f32_e32 v124, v124
	s_waitcnt lgkmcnt(6)
	v_mfma_f32_32x32x16_bf16 v[64:79], v[2:5], v[128:131], v[64:79]
	v_add_f32_e32 v251, v251, v123
	v_exp_f32_e32 v125, v125
	v_add_f32_e32 v248, v248, v124
	v_exp_f32_e32 v126, v126
	v_mfma_f32_32x32x16_bf16 v[48:63], v[6:9], v[128:131], v[48:63]
	v_add_f32_e32 v249, v249, v125
	v_exp_f32_e32 v127, v127
	v_add_f32_e32 v250, v250, v126
	v_add_f32_e32 v251, v251, v127
	s_waitcnt lgkmcnt(4)
	v_mfma_f32_32x32x16_bf16 v[64:79], v[10:13], v[136:139], v[64:79]
	v_cvt_pk_bf16_f32 v234, v112, v113
	v_cvt_pk_bf16_f32 v235, v114, v115
	v_cvt_pk_bf16_f32 v236, v116, v117
	v_cvt_pk_bf16_f32 v237, v118, v119
	v_mfma_f32_32x32x16_bf16 v[48:63], v[198:201], v[136:139], v[48:63]
	v_cvt_pk_bf16_f32 v238, v120, v121
	v_cvt_pk_bf16_f32 v239, v122, v123
	v_cvt_pk_bf16_f32 v240, v124, v125
	v_cvt_pk_bf16_f32 v241, v126, v127
	s_cmp_eq_u32 s75, 3
	s_cbranch_scc1 .Lfa_bs_w3
	s_cmp_eq_u32 s75, 2
	s_cbranch_scc1 .Lfa_bs_w2
	s_waitcnt vmcnt(4)
	s_branch .Lfa_bs_wj

; __device__ __forceinline__ void attn_unit(const Args& a, int l, int b, int h, int R0, bool special, LAS unsigned char* lds, float kb, int wv, bool pre, bool hasn, int nb, int nh, int nR0) {
;     ...
;     if (wave >= 4) __builtin_amdgcn_s_setprio(1);
.Lfa_a_nov:
	s_add_u32 s34, s34, 0x80
	s_addc_u32 s35, s35, 0
	s_mov_b32 s1, s30
	s_add_i32 s30, s30, 0x2400
	s_cmp_eq_u32 s30, 0x6c00
	s_cselect_b32 s30, 0, s30
	s_mov_b32 s31, s1
	v_add_f32_e32 v249, v249, v101
	v_exp_f32_e32 v103, v103
	v_add_f32_e32 v250, v250, v102
	v_add_f32_e32 v251, v251, v103
	s_waitcnt lgkmcnt(10)
	v_mfma_f32_32x32x16_bf16 v[128:143], v[2:5], v[156:159], v[32:47]
	v_cvt_pk_bf16_f32 v96, v96, v97
	v_cvt_pk_bf16_f32 v97, v98, v99
	v_cvt_pk_bf16_f32 v98, v100, v101
	v_cvt_pk_bf16_f32 v99, v102, v103
	v_mfma_f32_32x32x16_bf16 v[112:127], v[6:9], v[156:159], v[32:47]
	ds_read_b128 v[2:5], v231
	ds_read_b128 v[6:9], v231 offset:4608
	v_exp_f32_e32 v104, v104
	v_exp_f32_e32 v105, v105
	v_add_f32_e32 v248, v248, v104
	v_exp_f32_e32 v106, v106
	s_waitcnt lgkmcnt(10)
	v_mfma_f32_32x32x16_bf16 v[128:143], v[10:13], v[160:163], v[128:143]
	v_add_f32_e32 v249, v249, v105
	v_exp_f32_e32 v107, v107
	v_add_f32_e32 v250, v250, v106
	v_exp_f32_e32 v108, v108
	v_mfma_f32_32x32x16_bf16 v[112:127], v[198:201], v[160:163], v[112:127]
	ds_read_b128 v[10:13], v231 offset:32
	ds_read_b128 v[198:201], v231 offset:4640
	v_add_f32_e32 v251, v251, v107
	v_exp_f32_e32 v109, v109
	v_add_f32_e32 v248, v248, v108
	v_exp_f32_e32 v110, v110
	s_waitcnt lgkmcnt(10)
	v_mfma_f32_32x32x16_bf16 v[128:143], v[202:205], v[164:167], v[128:143]
	v_add_f32_e32 v249, v249, v109
	v_exp_f32_e32 v111, v111
	v_add_f32_e32 v250, v250, v110
	v_add_f32_e32 v251, v251, v111
	v_mfma_f32_32x32x16_bf16 v[112:127], v[206:209], v[164:167], v[112:127]
	v_cvt_pk_bf16_f32 v104, v104, v105
	v_cvt_pk_bf16_f32 v105, v106, v107
	v_cvt_pk_bf16_f32 v106, v108, v109
	v_cvt_pk_bf16_f32 v107, v110, v111
	s_waitcnt lgkmcnt(8)
	v_mfma_f32_32x32x16_bf16 v[128:143], v[210:213], v[144:147], v[128:143]
	v_exp_f32_e32 v80, v80
	v_exp_f32_e32 v81, v81
	v_add_f32_e32 v248, v248, v80
	v_exp_f32_e32 v82, v82
	v_mfma_f32_32x32x16_bf16 v[112:127], v[214:217], v[144:147], v[112:127]
	ds_read_b128 v[210:213], v231 offset:64
	ds_read_b128 v[214:217], v231 offset:4672
	v_add_f32_e32 v249, v249, v81
	v_exp_f32_e32 v83, v83
	v_add_f32_e32 v250, v250, v82
	v_exp_f32_e32 v84, v84
	s_waitcnt lgkmcnt(8)
	v_mfma_f32_32x32x16_bf16 v[128:143], v[218:221], v[148:151], v[128:143]
	v_add_f32_e32 v251, v251, v83
	v_exp_f32_e32 v85, v85
	v_add_f32_e32 v248, v248, v84
	v_exp_f32_e32 v86, v86
	v_mfma_f32_32x32x16_bf16 v[112:127], v[222:225], v[148:151], v[112:127]
	ds_read_b128 v[218:221], v231 offset:96
	ds_read_b128 v[222:225], v231 offset:4704
	v_add_f32_e32 v249, v249, v85
	v_exp_f32_e32 v87, v87
	v_add_f32_e32 v250, v250, v86
	v_add_f32_e32 v251, v251, v87
	s_waitcnt lgkmcnt(8)
	v_mfma_f32_32x32x16_bf16 v[128:143], v[234:237], v[152:155], v[128:143]
	v_exp_f32_e32 v88, v88
	v_exp_f32_e32 v89, v89
	v_add_f32_e32 v248, v248, v88
	v_exp_f32_e32 v90, v90
	v_mfma_f32_32x32x16_bf16 v[112:127], v[238:241], v[152:155], v[112:127]
	v_add_f32_e32 v249, v249, v89
	v_exp_f32_e32 v91, v91
	v_add_f32_e32 v250, v250, v90
	v_exp_f32_e32 v92, v92
	s_waitcnt lgkmcnt(6)
	v_mfma_f32_32x32x16_bf16 v[64:79], v[2:5], v[96:99], v[64:79]
	v_add_f32_e32 v251, v251, v91
	v_exp_f32_e32 v93, v93
	v_add_f32_e32 v248, v248, v92
	v_exp_f32_e32 v94, v94
	v_mfma_f32_32x32x16_bf16 v[48:63], v[6:9], v[96:99], v[48:63]
	v_add_f32_e32 v249, v249, v93
	v_exp_f32_e32 v95, v95
	v_add_f32_e32 v250, v250, v94
	v_add_f32_e32 v251, v251, v95
	s_waitcnt lgkmcnt(4)
	v_mfma_f32_32x32x16_bf16 v[64:79], v[10:13], v[104:107], v[64:79]
	v_cvt_pk_bf16_f32 v234, v80, v81
	v_cvt_pk_bf16_f32 v235, v82, v83
	v_cvt_pk_bf16_f32 v236, v84, v85
	v_cvt_pk_bf16_f32 v237, v86, v87
	v_mfma_f32_32x32x16_bf16 v[48:63], v[198:201], v[104:107], v[48:63]
	v_cvt_pk_bf16_f32 v238, v88, v89
	v_cvt_pk_bf16_f32 v239, v90, v91
	v_cvt_pk_bf16_f32 v240, v92, v93
	v_cvt_pk_bf16_f32 v241, v94, v95
	s_sub_i32 s0, s84, 64
	s_cmp_le_i32 s0, s74
	s_cbranch_scc0 .Lfa_mask_a

; __device__ __forceinline__ void attn_unit(const Args& a, int l, int b, int h, int R0, bool special, LAS unsigned char* lds, float kb, int wv, bool pre, bool hasn, int nb, int nh, int nR0) {
;     ...
;     if (wave >= 4) __builtin_amdgcn_s_setprio(1);
.Lfa_b_nov:
	s_add_u32 s34, s34, 0x80
	s_addc_u32 s35, s35, 0
	s_mov_b32 s1, s30
	s_add_i32 s30, s30, 0x2400
	s_cmp_eq_u32 s30, 0x6c00
	s_cselect_b32 s30, 0, s30
	s_mov_b32 s31, s1
	v_add_f32_e32 v249, v249, v133
	v_exp_f32_e32 v135, v135
	v_add_f32_e32 v250, v250, v134
	v_add_f32_e32 v251, v251, v135
	s_waitcnt lgkmcnt(10)
	v_mfma_f32_32x32x16_bf16 v[96:111], v[2:5], v[156:159], v[32:47]
	v_cvt_pk_bf16_f32 v128, v128, v129
	v_cvt_pk_bf16_f32 v129, v130, v131
	v_cvt_pk_bf16_f32 v130, v132, v133
	v_cvt_pk_bf16_f32 v131, v134, v135
	v_mfma_f32_32x32x16_bf16 v[80:95], v[6:9], v[156:159], v[32:47]
	ds_read_b128 v[2:5], v231
	ds_read_b128 v[6:9], v231 offset:4608
	v_exp_f32_e32 v136, v136
	v_exp_f32_e32 v137, v137
	v_add_f32_e32 v248, v248, v136
	v_exp_f32_e32 v138, v138
	s_waitcnt lgkmcnt(10)
	v_mfma_f32_32x32x16_bf16 v[96:111], v[10:13], v[160:163], v[96:111]
	v_add_f32_e32 v249, v249, v137
	v_exp_f32_e32 v139, v139
	v_add_f32_e32 v250, v250, v138
	v_exp_f32_e32 v140, v140
	v_mfma_f32_32x32x16_bf16 v[80:95], v[198:201], v[160:163], v[80:95]
	ds_read_b128 v[10:13], v231 offset:32
	ds_read_b128 v[198:201], v231 offset:4640
	v_add_f32_e32 v251, v251, v139
	v_exp_f32_e32 v141, v141
	v_add_f32_e32 v248, v248, v140
	v_exp_f32_e32 v142, v142
	s_waitcnt lgkmcnt(10)
	v_mfma_f32_32x32x16_bf16 v[96:111], v[202:205], v[164:167], v[96:111]
	v_add_f32_e32 v249, v249, v141
	v_exp_f32_e32 v143, v143
	v_add_f32_e32 v250, v250, v142
	v_add_f32_e32 v251, v251, v143
	v_mfma_f32_32x32x16_bf16 v[80:95], v[206:209], v[164:167], v[80:95]
	v_cvt_pk_bf16_f32 v136, v136, v137
	v_cvt_pk_bf16_f32 v137, v138, v139
	v_cvt_pk_bf16_f32 v138, v140, v141
	v_cvt_pk_bf16_f32 v139, v142, v143
	s_waitcnt lgkmcnt(8)
	v_mfma_f32_32x32x16_bf16 v[96:111], v[210:213], v[144:147], v[96:111]
	v_exp_f32_e32 v112, v112
	v_exp_f32_e32 v113, v113
	v_add_f32_e32 v248, v248, v112
	v_exp_f32_e32 v114, v114
	v_mfma_f32_32x32x16_bf16 v[80:95], v[214:217], v[144:147], v[80:95]
	ds_read_b128 v[210:213], v231 offset:64
	ds_read_b128 v[214:217], v231 offset:4672
	v_add_f32_e32 v249, v249, v113
	v_exp_f32_e32 v115, v115
	v_add_f32_e32 v250, v250, v114
	v_exp_f32_e32 v116, v116
	s_waitcnt lgkmcnt(8)
	v_mfma_f32_32x32x16_bf16 v[96:111], v[218:221], v[148:151], v[96:111]
	v_add_f32_e32 v251, v251, v115
	v_exp_f32_e32 v117, v117
	v_add_f32_e32 v248, v248, v116
	v_exp_f32_e32 v118, v118
	v_mfma_f32_32x32x16_bf16 v[80:95], v[222:225], v[148:151], v[80:95]
	ds_read_b128 v[218:221], v231 offset:96
	ds_read_b128 v[222:225], v231 offset:4704
	v_add_f32_e32 v249, v249, v117
	v_exp_f32_e32 v119, v119
	v_add_f32_e32 v250, v250, v118
	v_add_f32_e32 v251, v251, v119
	s_waitcnt lgkmcnt(8)
	v_mfma_f32_32x32x16_bf16 v[96:111], v[234:237], v[152:155], v[96:111]
	v_exp_f32_e32 v120, v120
	v_exp_f32_e32 v121, v121
	v_add_f32_e32 v248, v248, v120
	v_exp_f32_e32 v122, v122
	v_mfma_f32_32x32x16_bf16 v[80:95], v[238:241], v[152:155], v[80:95]
	v_add_f32_e32 v249, v249, v121
	v_exp_f32_e32 v123, v123
	v_add_f32_e32 v250, v250, v122
	v_exp_f32_e32 v124, v124
	s_waitcnt lgkmcnt(6)
	v_mfma_f32_32x32x16_bf16 v[64:79], v[2:5], v[128:131], v[64:79]
	v_add_f32_e32 v251, v251, v123
	v_exp_f32_e32 v125, v125
	v_add_f32_e32 v248, v248, v124
	v_exp_f32_e32 v126, v126
	v_mfma_f32_32x32x16_bf16 v[48:63], v[6:9], v[128:131], v[48:63]
	v_add_f32_e32 v249, v249, v125
	v_exp_f32_e32 v127, v127
	v_add_f32_e32 v250, v250, v126
	v_add_f32_e32 v251, v251, v127
	s_waitcnt lgkmcnt(4)
	v_mfma_f32_32x32x16_bf16 v[64:79], v[10:13], v[136:139], v[64:79]
	v_cvt_pk_bf16_f32 v234, v112, v113
	v_cvt_pk_bf16_f32 v235, v114, v115
	v_cvt_pk_bf16_f32 v236, v116, v117
	v_cvt_pk_bf16_f32 v237, v118, v119
	v_mfma_f32_32x32x16_bf16 v[48:63], v[198:201], v[136:139], v[48:63]
	v_cvt_pk_bf16_f32 v238, v120, v121
	v_cvt_pk_bf16_f32 v239, v122, v123
	v_cvt_pk_bf16_f32 v240, v124, v125
	v_cvt_pk_bf16_f32 v241, v126, v127
	s_cmp_le_i32 s84, s74
	s_cbranch_scc0 .Lfa_mask_b
